# as v10 plus the waves 0-3 row-sum adds inside the P.V MFMA gaps written as scalar v_add_f32 instead of v_pk_add_f32
# speedup vs baseline: 1.0068x; 1.0068x over previous
; __device__ __forceinline__ unsigned cvt_pk_bf16(float lo, float hi) { unsigned r; asm volatile("v_cvt_pk_bf16_f32 %0, %1, %2" : "=v"(r) : "v"(lo), "v"(hi)); return r; }
; template <int MODE> __device__ __forceinline__ void attn_unit(const Unit& a, char* shm) {
;     ...
; #pragma unroll
;             for (int r = 0; r < 16; ++r) { p0[r] = __builtin_amdgcn_exp2f(p0[r]); p1[r] = __builtin_amdgcn_exp2f(p1[r]); }
;             f32x2 s2a = (f32x2){p0[0], p0[1]}, s2b = (f32x2){p1[0], p1[1]};
; #pragma unroll
;             for (int k2 = 1; k2 < 8; ++k2) { s2a += (f32x2){p0[2 * k2], p0[2 * k2 + 1]}; s2b += (f32x2){p1[2 * k2], p1[2 * k2 + 1]}; }
;             s2a += s2b;
;             l_reg += s2a.x + s2a.y;
; #pragma unroll
;             for (int kk = 0; kk < 4; ++kk) { pw[0][kk] = cvt_pk_bf16(p0[2 * kk], p0[2 * kk + 1]); pw[1][kk] = cvt_pk_bf16(p0[8 + 2 * kk], p0[8 + 2 * kk + 1]);
;                 pw[2][kk] = cvt_pk_bf16(p1[2 * kk], p1[2 * kk + 1]); pw[3][kk] = cvt_pk_bf16(p1[8 + 2 * kk], p1[8 + 2 * kk + 1]); }
;             if (g == 0) ATT_PV(pw, sv); else pend = true;
.LBB0_1920:
	v_exp_f32_e32 v128, v48
	v_exp_f32_e32 v122, v64
	v_exp_f32_e32 v129, v49
	v_exp_f32_e32 v123, v65
	v_exp_f32_e32 v140, v50
	v_exp_f32_e32 v138, v66
	v_exp_f32_e32 v141, v51
	v_exp_f32_e32 v139, v67
	v_exp_f32_e32 v136, v52
	v_exp_f32_e32 v126, v68
	v_exp_f32_e32 v137, v53
	v_exp_f32_e32 v127, v69
	v_exp_f32_e32 v124, v54
	v_exp_f32_e32 v120, v70
	v_exp_f32_e32 v125, v55
	v_exp_f32_e32 v121, v71
	v_exp_f32_e32 v118, v56
	v_exp_f32_e32 v116, v72
	v_exp_f32_e32 v119, v57
	v_exp_f32_e32 v117, v73
	v_exp_f32_e32 v114, v58
	v_exp_f32_e32 v72, v74
	v_exp_f32_e32 v115, v59
	v_exp_f32_e32 v73, v75
	v_exp_f32_e32 v70, v60
	v_exp_f32_e32 v68, v76
	v_exp_f32_e32 v71, v61
	v_exp_f32_e32 v69, v77
	v_exp_f32_e32 v66, v62
	v_exp_f32_e32 v64, v78
	v_exp_f32_e32 v67, v63
	v_exp_f32_e32 v65, v79
	ds_read_b64_tr_b16 v[158:159], v149 offset:31744
	ds_read_b64_tr_b16 v[160:161], v149 offset:32256
	s_andn2_b64 vcc, exec, s[44:45]
	v_cvt_pk_bf16_f32 v60, v128, v129
	v_cvt_pk_bf16_f32 v56, v118, v119
	v_cvt_pk_bf16_f32 v52, v122, v123
	v_cvt_pk_bf16_f32 v48, v116, v117
	v_cvt_pk_bf16_f32 v61, v140, v141
	v_cvt_pk_bf16_f32 v57, v114, v115
	v_cvt_pk_bf16_f32 v53, v138, v139
	v_cvt_pk_bf16_f32 v49, v72, v73
	v_cvt_pk_bf16_f32 v62, v136, v137
	v_cvt_pk_bf16_f32 v58, v70, v71
	v_cvt_pk_bf16_f32 v54, v126, v127
	v_cvt_pk_bf16_f32 v50, v68, v69
	v_cvt_pk_bf16_f32 v63, v124, v125
	v_cvt_pk_bf16_f32 v59, v66, v67
	v_cvt_pk_bf16_f32 v55, v120, v121
	v_cvt_pk_bf16_f32 v51, v64, v65
	s_cbranch_vccnz .LBB0_1922
	s_waitcnt lgkmcnt(0)
	v_mfma_f32_32x32x16_bf16 v[0:15], v[60:63], v[230:233], v[0:15]
	v_add_f32_e32 v74, v128, v140
	v_add_f32_e32 v75, v129, v141
	v_add_f32_e32 v76, v122, v138
	v_add_f32_e32 v77, v123, v139
	v_mfma_f32_32x32x16_bf16 v[0:15], v[56:59], v[234:237], v[0:15]
	v_add_f32_e32 v74, v136, v74
	v_add_f32_e32 v75, v137, v75
	v_add_f32_e32 v76, v126, v76
	v_add_f32_e32 v77, v127, v77
	v_mfma_f32_32x32x16_bf16 v[0:15], v[52:55], v[238:241], v[0:15]
	v_add_f32_e32 v74, v124, v74
	v_add_f32_e32 v75, v125, v75
	v_add_f32_e32 v76, v120, v76
	v_add_f32_e32 v77, v121, v77
	v_mfma_f32_32x32x16_bf16 v[0:15], v[48:51], v[242:245], v[0:15]
	v_add_f32_e32 v74, v118, v74
	v_add_f32_e32 v75, v119, v75
	v_add_f32_e32 v76, v116, v76
	v_add_f32_e32 v77, v117, v77
	v_mfma_f32_32x32x16_bf16 v[16:31], v[60:63], v[246:249], v[16:31]
	v_add_f32_e32 v74, v114, v74
	v_add_f32_e32 v75, v115, v75
	v_add_f32_e32 v72, v72, v76
	v_add_f32_e32 v73, v73, v77
	v_mfma_f32_32x32x16_bf16 v[16:31], v[56:59], v[150:153], v[16:31]
	v_add_f32_e32 v70, v70, v74
	v_add_f32_e32 v71, v71, v75
	v_add_f32_e32 v68, v68, v72
	v_add_f32_e32 v69, v69, v73
	v_mfma_f32_32x32x16_bf16 v[16:31], v[52:55], v[154:157], v[16:31]
	v_add_f32_e32 v66, v66, v70
	v_add_f32_e32 v67, v67, v71
	v_add_f32_e32 v64, v64, v68
	v_add_f32_e32 v65, v65, v69
	v_mfma_f32_32x32x16_bf16 v[16:31], v[48:51], v[158:161], v[16:31]
	v_add_f32_e32 v64, v64, v66
	v_add_f32_e32 v65, v65, v67
	v_add_f32_e32 v64, v64, v65
	v_add_f32_e32 v64, v113, v64
	s_branch .Lmla_sumdone
